# diff-attn Q frags d0-2 held in v244-255 instead of LDS re-reads
# baseline (speedup 1.0000x reference)
; __device__ __forceinline__ bf16x8 kld(lds_cptr p) { return *(const __attribute__((address_space(3))) bf16x8*)p; }
; #define WAIT_BAR(N) asm volatile("s_waitcnt vmcnt(" #N ") lgkmcnt(0)\n\ts_barrier" ::: "memory")
; #define SJ_ISSUE() do { if (sj < SJ.n) { att::side_issue(SJ, sj, wid, lane, shm); sjp = true; sji = true; } } while (0)
; template <int THRL> ...
;     ...
;     __syncthreads();
;     DMA_K(0, KSL(0)); DMA_V(0, 0); DMA_K(1, KSL(1));
;     { bf16x8 qr[4];
; #pragma unroll
;       for (int d0 = 0; d0 < 4; ++d0) qr[d0] = att::ld8(Qw + d0 * 16);
; #pragma unroll
;       for (int d0 = 0; d0 < 4; ++d0) *(__attribute__((address_space(3))) bf16x8*)(qp0 + d0 * 1024) = qr[d0]; }
;     float zf_ = 0.f; asm volatile("" : "+v"(zf_));
;     f32x16 zv_;
; #pragma unroll
;     for (int r = 0; r < 16; ++r) zv_[r] = zf_;
;     float mhat = 0.f, l_reg = 0.f; f32x16 o[4]; o[0] = zv_; o[1] = zv_; o[2] = zv_; o[3] = zv_; f32x16 negm = zv_; asm volatile("" : "+v"(negm));
;     bool resc = false;
;     ...
;     f32x16 pA0, pA1, pB0, pB1;
;     int sl_prev = 0, sl_cur = 0, sl_next = VSLOT;
;     ...
;     DMA_K(2, KSL(2));
;     WAIT_BAR(4);
;     { const lds_cptr kb = kp0 + KSL(0);
; #pragma unroll
;       for (int d0 = 0; d0 < 4; ++d0) { const bf16x8 b0 = kld(kb + d0 * 2048), b1 = kld(kb + d0 * 2048 + 512), q0 = kld(qp0 + d0 * 1024);
;         if (d0 == 0) { pA0 = __builtin_amdgcn_mfma_f32_32x32x16_bf16(b0, q0, negm, 0, 0, 0); pA1 = __builtin_amdgcn_mfma_f32_32x32x16_bf16(b1, q0, negm, 0, 0, 0); }
;         else { pA0 = __builtin_amdgcn_mfma_f32_32x32x16_bf16(b0, q0, pA0, 0, 0, 0); pA1 = __builtin_amdgcn_mfma_f32_32x32x16_bf16(b1, q0, pA1, 0, 0, 0); } }
;       float rm = pA0[0];
; #pragma unroll
;       for (int r = 1; r < 16; ++r) rm = __builtin_fmaxf(rm, pA0[r]);
; #pragma unroll
;       for (int r = 0; r < 16; ++r) rm = __builtin_fmaxf(rm, pA1[r]);
;       { auto rr = __builtin_amdgcn_permlane32_swap(__float_as_uint(rm), __float_as_uint(rm), false, false); rm = __builtin_fmaxf(__uint_as_float(rr[0]), __uint_as_float(rr[1])); }
;       mhat = rm;
; #pragma unroll
;       for (int r = 0; r < 16; ++r) { pA0[r] = __builtin_amdgcn_exp2f(pA0[r] - rm); pA1[r] = __builtin_amdgcn_exp2f(pA1[r] - rm); }
; #pragma unroll
;       for (int r = 0; r < 16; ++r) negm[r] = -mhat;
;       asm volatile("" : "+v"(negm)); }
;     WAIT_BAR(0);
;     SJ_ISSUE(); DMA_K(3, KSL(3)); DMA_V(1, VSLOT);
.LBB0_403:
	s_or_b32 s28, s2, s50
	s_ashr_i32 s29, s28, 31
	s_lshl_b32 s0, s2, 7
	s_lshl_b64 s[28:29], s[28:29], 19
	s_cmp_lg_u32 0, -1
	v_lshl_add_u64 v[2:3], v[154:155], 0, s[0:1]
	s_cselect_b32 s0, 0, 0
	v_lshl_add_u64 v[50:51], v[156:157], 0, s[28:29]
	s_waitcnt lgkmcnt(0)
	s_barrier
	s_mov_b32 m0, s89
	s_nop 0
	global_load_lds_dwordx4 v[50:51], off
	s_add_i32 s28, s0, s96
	s_mov_b32 m0, s97
	s_nop 0
	global_load_lds_dwordx4 v[150:151], off
	s_add_i32 s28, s28, 0x8400
	s_mov_b32 m0, s28
	s_nop 0
	global_load_lds_dwordx4 v[158:159], off
	s_mov_b64 s[28:29], 0x2000
	s_add_i32 s0, s0, s81
	v_lshl_add_u64 v[4:5], v[50:51], 0, s[28:29]
	s_add_i32 s28, s0, 0x2000
	s_mov_b32 m0, s28
	s_nop 0
	global_load_lds_dwordx4 v[4:5], off
	global_load_dwordx4 v[4:7], v[2:3], off
	global_load_dwordx4 v[8:11], v[2:3], off offset:32
	global_load_dwordx4 v[12:15], v[2:3], off offset:64
	global_load_dwordx4 v[16:19], v[2:3], off offset:96
	v_add_u32_e32 v201, s77, v148
	v_mov_b32_e32 v2, v147
	v_lshl_add_u64 v[34:35], v[50:51], 0, s[16:17]
	s_addk_i32 s0, 0x4000
	s_cmp_lt_i32 s88, s3
	s_cselect_b64 s[28:29], -1, 0
	s_cmp_ge_i32 s88, s3
	s_cselect_b64 s[30:31], -1, 0
	s_and_b64 vcc, exec, s[30:31]
	s_waitcnt vmcnt(3)
	ds_write_b128 v201, v[4:7]
	s_waitcnt vmcnt(2)
	ds_write_b128 v201, v[8:11] offset:1024
	s_waitcnt vmcnt(1)
	ds_write_b128 v201, v[12:15] offset:2048
	s_waitcnt vmcnt(0)
	ds_write_b128 v201, v[16:19] offset:3072
	s_nop 0
	v_mov_b32_e32 v16, v2
	v_mov_b32_e32 v17, v2
	v_mov_b32_e32 v3, v2
	v_mov_b32_e32 v4, v2
	v_mov_b32_e32 v5, v2
	v_mov_b32_e32 v6, v2
	v_mov_b32_e32 v7, v2
	v_mov_b32_e32 v8, v2
	v_mov_b32_e32 v9, v2
	v_mov_b32_e32 v10, v2
	v_mov_b32_e32 v11, v2
	v_mov_b32_e32 v12, v2
	v_mov_b32_e32 v13, v2
	v_mov_b32_e32 v14, v2
	v_mov_b32_e32 v15, v2
	v_mov_b64_e32 v[32:33], v[16:17]
	v_mov_b64_e32 v[30:31], v[14:15]
	v_mov_b64_e32 v[28:29], v[12:13]
	v_mov_b64_e32 v[26:27], v[10:11]
	v_mov_b64_e32 v[24:25], v[8:9]
	v_mov_b64_e32 v[22:23], v[6:7]
	v_mov_b64_e32 v[20:21], v[4:5]
	v_mov_b64_e32 v[18:19], v[2:3]
	s_mov_b32 m0, s0
	s_nop 0
	global_load_lds_dwordx4 v[34:35], off
	s_waitcnt vmcnt(4) lgkmcnt(0)
	s_barrier
	ds_read_b128 v[244:247], v201
	ds_read_b128 v[248:251], v201 offset:1024
	ds_read_b128 v[252:255], v201 offset:2048
	ds_read_b128 v[52:55], v191
	ds_read_b128 v[56:59], v201
	ds_read_b128 v[60:63], v201 offset:1024
	ds_read_b128 v[64:67], v191 offset:512
	s_waitcnt lgkmcnt(2)
	v_mfma_f32_32x32x16_bf16 v[34:49], v[52:55], v[56:59], v[18:33]
	s_waitcnt lgkmcnt(0)
	v_mfma_f32_32x32x16_bf16 v[18:33], v[64:67], v[56:59], v[18:33]
	ds_read_b128 v[52:55], v191 offset:2048
	ds_read_b128 v[56:59], v191 offset:2560
	s_waitcnt lgkmcnt(1)
	v_mfma_f32_32x32x16_bf16 v[34:49], v[52:55], v[60:63], v[34:49]
	s_waitcnt lgkmcnt(0)
	v_mfma_f32_32x32x16_bf16 v[18:33], v[56:59], v[60:63], v[18:33]
	ds_read_b128 v[52:55], v191 offset:4096
	ds_read_b128 v[56:59], v201 offset:2048
	ds_read_b128 v[60:63], v201 offset:3072
	ds_read_b128 v[64:67], v191 offset:4608
	s_waitcnt lgkmcnt(2)
	v_mfma_f32_32x32x16_bf16 v[34:49], v[52:55], v[56:59], v[34:49]
	s_waitcnt lgkmcnt(0)
	v_mfma_f32_32x32x16_bf16 v[18:33], v[64:67], v[56:59], v[18:33]
	ds_read_b128 v[52:55], v191 offset:6144
	ds_read_b128 v[56:59], v191 offset:6656
	s_waitcnt lgkmcnt(1)
	v_mfma_f32_32x32x16_bf16 v[34:49], v[52:55], v[60:63], v[34:49]
	s_waitcnt lgkmcnt(0)
	v_mfma_f32_32x32x16_bf16 v[18:33], v[56:59], v[60:63], v[18:33]
	s_nop 9
	v_max_f32_e32 v52, v35, v35
	v_max_f32_e32 v53, v34, v34
	v_max_f32_e32 v52, v53, v52
	v_max3_f32 v52, v52, v36, v37
	v_max3_f32 v52, v52, v38, v39
	v_max3_f32 v52, v52, v40, v41
	v_max3_f32 v52, v52, v42, v43
	v_max3_f32 v52, v52, v44, v45
	v_max3_f32 v52, v52, v46, v47
	v_max3_f32 v52, v52, v48, v49
	v_max3_f32 v52, v52, v18, v19
	v_max3_f32 v52, v52, v20, v21
	v_max3_f32 v52, v52, v22, v23
	v_max3_f32 v52, v52, v24, v25
	v_max3_f32 v52, v52, v26, v27
	v_max3_f32 v52, v52, v28, v29
	v_max3_f32 v52, v52, v30, v31
	v_max3_f32 v52, v52, v32, v33
	v_mov_b32_e32 v53, v52
	s_nop 1
	v_permlane32_swap_b32_e32 v52, v53
	v_max_f32_e32 v53, v53, v53
	v_max_f32_e32 v52, v52, v52
	v_max_f32_e32 v149, v52, v53
	v_xor_b32_e32 v66, 0x80000000, v149
	v_mov_b32_e32 v67, v66
	v_mov_b32_e32 v68, v66
	v_mov_b32_e32 v69, v66
	v_mov_b32_e32 v70, v66
	v_mov_b32_e32 v71, v66
	v_mov_b32_e32 v72, v66
	v_mov_b32_e32 v73, v66
	v_mov_b32_e32 v74, v66
	v_mov_b32_e32 v75, v66
	v_mov_b32_e32 v76, v66
	v_mov_b32_e32 v77, v66
	v_mov_b32_e32 v78, v66
	v_mov_b32_e32 v79, v66
	v_mov_b32_e32 v80, v66
	v_mov_b32_e32 v81, v66
	s_waitcnt vmcnt(0) lgkmcnt(0)
	s_barrier
	s_cbranch_vccnz .LBB0_413
	s_lshl_b32 s0, s88, 8
	s_add_i32 s0, s0, s76
	s_cmpk_gt_i32 s0, 0x3ff
	s_cbranch_scc0 .LBB0_407
	s_lshl_b32 s41, s0, 6
	s_cmpk_gt_u32 s0, 0x13ff
	s_cbranch_scc0 .LBB0_408
	s_lshl_b32 s34, s0, 1
	s_add_i32 s34, s34, 0x7fffd800
	s_and_b32 s38, s34, 0x7fffffc0
	s_and_b32 s39, s41, 0x7c0
	s_mov_b64 s[34:35], s[64:65]
	s_mov_b32 s40, 11
	s_cbranch_execz .LBB0_409
	s_branch .LBB0_410

; __device__ __forceinline__ bf16x8 kld(lds_cptr p) { return *(const __attribute__((address_space(3))) bf16x8*)p; }
; #define SJ_ISSUE() do { if (sj < SJ.n) { att::side_issue(SJ, sj, wid, lane, shm); sjp = true; sji = true; } } while (0)
; #define SJ_WAIT_BAR() do { if (sji) { WAIT_BAR(5); sji = false; } else { WAIT_BAR(3); } } while (0)
; #define DMA_K(t_, slot) att::glds16(ksrc + (size_t)(t_) * 8 * 512, (unsigned)__builtin_amdgcn_readfirstlane(kdst + (slot)))
; #define DMA_V(t_, slot) do { att::glds16(vsrc + (size_t)(t_) * 16 * 512, (unsigned)__builtin_amdgcn_readfirstlane(vdst + (slot))); \
;     att::glds16(vsrc + (size_t)(t_) * 16 * 512 + 512, (unsigned)__builtin_amdgcn_readfirstlane(vdst + (slot) + 1024)); } while (0)
; #define ROT() do { sl_prev = sl_cur; sl_cur = sl_next; sl_next = (sl_next == 2 * VSLOT) ? 0 : sl_next + VSLOT; } while (0)
; template <int THRL> ...
;     ...
;     SJ_ISSUE(); DMA_K(3, KSL(3)); DMA_V(1, VSLOT);
;     ROT();
;     bf16x8 kq0, kq1, kq2, kq3, qq0, qq1;
;     kq0 = kld(kp0 + KSL(1)); kq1 = kld(kp0 + KSL(1) + 512); kq2 = kld(kp0 + KSL(1) + 2048); qq0 = kld(qp0);
;     SJ_WAIT_BAR();
.LBB0_413:
	s_cmp_lg_u32 0, -1
	s_mov_b64 s[34:35], 0x6000
	s_cselect_b32 s0, 0, 0
	v_lshl_add_u64 v[52:53], v[50:51], 0, s[34:35]
	s_add_i32 s34, s0, s81
	s_addk_i32 s34, 0x6000
	s_mov_b32 m0, s34
	s_nop 0
	global_load_lds_dwordx4 v[52:53], off
	s_add_i32 s0, s0, s96
	s_add_i32 s34, s0, 0xc000
	s_mov_b32 m0, s34
	s_nop 0
	global_load_lds_dwordx4 v[160:161], off
	s_add_i32 s0, s0, 0xc400
	s_mov_b32 m0, s0
	s_nop 0
	global_load_lds_dwordx4 v[162:163], off
	ds_read_b128 v[82:85], v191 offset:8192
	ds_read_b128 v[134:137], v191 offset:8704
	ds_read_b128 v[130:133], v191 offset:10240
	s_mov_b64 s[34:35], -1
	s_and_b64 vcc, exec, s[30:31]
	s_cbranch_vccz .LBB0_415
	s_waitcnt vmcnt(3) lgkmcnt(0)
	s_barrier
	s_mov_b64 s[34:35], 0

.LBB0_418:
	v_add_u32_e32 v225, s34, v192
	s_add_i32 s34, s30, 0x2000
	s_and_b32 s55, s34, 0x6000
	v_add_u32_e32 v114, s55, v191
	ds_read_b128 v[226:229], v114 offset:2560
	v_add_f32_e32 v86, v98, v99
	v_cvt_pk_bf16_f32 v126, v98, v99
	s_waitcnt lgkmcnt(1)
	v_mfma_f32_32x32x16_bf16 v[98:113], v[82:85], v[244:247], v[66:81]
	v_add_f32_e32 v86, v127, v86
	v_add_f32_e32 v86, v223, v86
	v_add_f32_e32 v86, v217, v86
	v_add_f32_e32 v86, v219, v86
	v_cvt_pk_bf16_f32 v127, v127, v223
	ds_read_b128 v[234:237], v114 offset:4096
	v_add_f32_e32 v82, v222, v86
	v_add_f32_e32 v82, v224, v82
	v_add_f32_e32 v82, v214, v82
	v_add_f32_e32 v115, v122, v82
	v_mfma_f32_32x32x16_bf16 v[82:97], v[134:137], v[244:247], v[66:81]
	v_cvt_pk_bf16_f32 v128, v217, v219
	v_cvt_pk_bf16_f32 v129, v222, v224
	ds_read_b128 v[134:137], v114 offset:4608
	s_waitcnt lgkmcnt(2)
	v_mfma_f32_32x32x16_bf16 v[98:113], v[130:133], v[248:251], v[98:113]
	v_add_f32_e32 v115, v123, v115
	v_add_f32_e32 v115, v220, v115
	v_add_f32_e32 v115, v216, v115
	v_add_f32_e32 v115, v218, v115
	v_cvt_pk_bf16_f32 v122, v214, v122
	v_cvt_pk_bf16_f32 v123, v123, v220
	ds_read_b128 v[130:133], v114 offset:6144
	v_mfma_f32_32x32x16_bf16 v[82:97], v[226:229], v[248:251], v[82:97]
	v_add_f32_e32 v115, v215, v115
	v_add_f32_e32 v115, v221, v115
	v_add_f32_e32 v115, v203, v115
	v_add_f32_e32 v115, v206, v115
	v_cvt_pk_bf16_f32 v124, v216, v218
	v_cvt_pk_bf16_f32 v125, v215, v221
	ds_read_b128 v[214:217], v114 offset:6656
	ds_read_b128 v[218:221], v201 offset:3072
	s_waitcnt lgkmcnt(3)
	v_mfma_f32_32x32x16_bf16 v[98:113], v[234:237], v[252:255], v[98:113]
	v_add_f32_e32 v114, v212, v115
	v_add_f32_e32 v114, v213, v114
	v_add_f32_e32 v114, v142, v114
	v_add_f32_e32 v114, v209, v114
	v_cvt_pk_bf16_f32 v118, v203, v206
	v_cvt_pk_bf16_f32 v119, v212, v213
	ds_read_b64_tr_b16 v[226:227], v225 offset:32768
	ds_read_b64_tr_b16 v[228:229], v225 offset:33280
	v_mfma_f32_32x32x16_bf16 v[82:97], v[134:137], v[252:255], v[82:97]
	v_add_f32_e32 v114, v204, v114
	v_add_f32_e32 v114, v207, v114
	v_add_f32_e32 v114, v144, v114
	v_add_f32_e32 v114, v202, v114
	v_cvt_pk_bf16_f32 v120, v142, v209
	v_cvt_pk_bf16_f32 v121, v204, v207
	ds_read_b64_tr_b16 v[134:135], v225 offset:36864
	ds_read_b64_tr_b16 v[136:137], v225 offset:37376
	s_waitcnt lgkmcnt(4)
	v_mfma_f32_32x32x16_bf16 v[98:113], v[130:133], v[218:221], v[98:113]
	v_add_f32_e32 v114, v205, v114
	v_add_f32_e32 v114, v210, v114
	v_add_f32_e32 v114, v143, v114
	v_add_f32_e32 v130, v145, v114
	v_cvt_pk_bf16_f32 v114, v144, v202
	v_cvt_pk_bf16_f32 v115, v205, v210
	ds_read_b64_tr_b16 v[138:139], v225 offset:40960
	ds_read_b64_tr_b16 v[140:141], v225 offset:41472
	v_mfma_f32_32x32x16_bf16 v[82:97], v[214:217], v[218:221], v[82:97]
	v_add_f32_e32 v116, v208, v130
	v_add_f32_e32 v130, v211, v116
	v_cvt_pk_bf16_f32 v116, v143, v145
	v_cvt_pk_bf16_f32 v117, v208, v211
	s_waitcnt lgkmcnt(4)
	v_mfma_f32_32x32x16_bf16 v[2:17], v[126:129], v[226:229], v[2:17]
	ds_read_b64_tr_b16 v[142:143], v225 offset:45056
	ds_read_b64_tr_b16 v[144:145], v225 offset:45568
	v_add_f32_e32 v202, v146, v130
	s_nop 2
	v_max3_f32 v130, v98, v99, v82
	v_max3_f32 v131, v100, v101, v83
	v_max3_f32 v130, v130, v84, v85
	v_max3_f32 v146, v130, v102, v103
	v_max3_f32 v203, v131, v104, v105
	s_waitcnt lgkmcnt(4)
	v_mfma_f32_32x32x16_bf16 v[50:65], v[126:129], v[134:137], v[50:65]
	ds_read_b64_tr_b16 v[130:131], v225 offset:33792
	ds_read_b64_tr_b16 v[132:133], v225 offset:34304
	s_add_i32 s34, s30, 0x8000
	s_and_b32 s34, s34, 0x6000
	v_lshl_add_u64 v[134:135], v[178:179], 0, s[30:31]
	s_add_i32 s34, s34, s89
	s_mov_b32 m0, s34
	s_nop 0
	global_load_lds_dwordx4 v[134:135], off
	v_max3_f32 v134, v146, v86, v87
	v_max3_f32 v135, v203, v88, v89
	v_max3_f32 v146, v134, v106, v107
	v_max3_f32 v203, v135, v108, v109
	s_waitcnt lgkmcnt(4)
	v_mfma_f32_32x32x16_bf16 v[34:49], v[126:129], v[138:141], v[34:49]
	s_movk_i32 s34, 0xc000
	s_mov_b32 s35, -1
	ds_read_b64_tr_b16 v[134:135], v225 offset:37888
	ds_read_b64_tr_b16 v[136:137], v225 offset:38400
	v_lshl_add_u64 v[138:139], v[180:181], 0, s[34:35]
	s_movk_i32 s34, 0xc400
	s_add_i32 s36, s2, s97
	s_mov_b32 m0, s36
	s_nop 0
	global_load_lds_dwordx4 v[138:139], off
	s_mov_b32 s35, -1
	v_lshl_add_u64 v[138:139], v[180:181], 0, s[34:35]
	s_add_i32 s34, s36, 0x400
	s_mov_b32 m0, s34
	s_nop 0
	global_load_lds_dwordx4 v[138:139], off
	v_max3_f32 v138, v146, v90, v91
	v_max3_f32 v139, v203, v92, v93
	v_max3_f32 v146, v138, v110, v111
	v_max3_f32 v203, v139, v112, v113
	s_waitcnt lgkmcnt(4)
	v_mfma_f32_32x32x16_bf16 v[18:33], v[126:129], v[142:145], v[18:33]
	v_max3_f32 v126, v146, v94, v95
	v_max3_f32 v127, v203, v96, v97
	ds_read_b64_tr_b16 v[138:139], v225 offset:41984
	ds_read_b64_tr_b16 v[140:141], v225 offset:42496
	v_max_f32 v126, v126, v127
	s_nop 0
	v_mov_b32_e32 v127, v126
	s_nop 1
	v_permlane32_swap_b32_e32 v126, v127
	v_max_f32 v126, v126, v127
	s_nop 0
	v_cmp_lt_f32_e32 vcc, s49, v126
	s_cmp_lg_u64 vcc, 0
	s_cselect_b64 s[36:37], -1, 0
	s_cbranch_vccnz .LBB0_451
; #define WAIT_BAR(N) asm volatile("s_waitcnt vmcnt(" #N ") lgkmcnt(0)\n\ts_barrier" ::: "memory")
; #define RESC() do { if (resc) { asm volatile("s_waitcnt lgkmcnt(0)" ::: "memory"); \
;       _Pragma("unroll") for (int d_ = 0; d_ < 4; ++d_) _Pragma("unroll") for (int r = 0; r < 16; ++r) o[d_][r] *= wsf[crow(r, hi)]; } } while (0)
; #define ROT() do { sl_prev = sl_cur; sl_cur = sl_next; sl_next = (sl_next == 2 * VSLOT) ? 0 : sl_next + VSLOT; } while (0)
; template <int THRL> ...
;     ...
;     int t = 1;
;     for (; t + 4 < NT; t += 2) {
;       STEP(pB0, pB1, pA0, pA1, t, true, true, true, false);                    WAIT_BAR(3);   RESC(); ROT();
.LBB0_419:
	s_add_u32 s34, s30, 0x4000
	s_addc_u32 s35, s31, 0
	s_and_b32 s38, s34, 0x6000
	s_waitcnt lgkmcnt(4)
	v_mfma_f32_32x32x16_bf16 v[2:17], v[122:125], v[130:133], v[2:17]
	ds_read_b64_tr_b16 v[214:215], v225 offset:46080
	ds_read_b64_tr_b16 v[216:217], v225 offset:46592
	v_exp_f32 v98, v98
	v_exp_f32 v99, v99
	v_exp_f32 v127, v100
	s_waitcnt lgkmcnt(4)
	v_mfma_f32_32x32x16_bf16 v[50:65], v[122:125], v[134:137], v[50:65]
	ds_read_b64_tr_b16 v[130:131], v225 offset:34816
	ds_read_b64_tr_b16 v[132:133], v225 offset:35328
	v_exp_f32 v206, v101
	v_exp_f32 v142, v102
	v_exp_f32 v144, v103
	s_waitcnt lgkmcnt(4)
	v_mfma_f32_32x32x16_bf16 v[34:49], v[122:125], v[138:141], v[34:49]
	ds_read_b64_tr_b16 v[100:101], v225 offset:38912
	ds_read_b64_tr_b16 v[102:103], v225 offset:39424
	v_exp_f32 v210, v104
	v_exp_f32 v212, v105
	v_exp_f32 v143, v106
	s_waitcnt lgkmcnt(4)
	v_mfma_f32_32x32x16_bf16 v[18:33], v[122:125], v[214:217], v[18:33]
	ds_read_b64_tr_b16 v[134:135], v225 offset:43008
	ds_read_b64_tr_b16 v[136:137], v225 offset:43520
	v_exp_f32 v122, v107
	v_exp_f32 v123, v108
	v_exp_f32 v209, v109
	s_waitcnt lgkmcnt(4)
	v_mfma_f32_32x32x16_bf16 v[2:17], v[118:121], v[130:133], v[2:17]
	ds_read_b64_tr_b16 v[104:105], v225 offset:47104
	ds_read_b64_tr_b16 v[106:107], v225 offset:47616
	v_exp_f32 v208, v110
	v_exp_f32 v211, v111
	v_exp_f32 v203, v112
	s_waitcnt lgkmcnt(4)
	v_mfma_f32_32x32x16_bf16 v[50:65], v[118:121], v[100:103], v[50:65]
	ds_read_b64_tr_b16 v[108:109], v225 offset:35840
	ds_read_b64_tr_b16 v[110:111], v225 offset:36352
	v_exp_f32 v220, v113
	v_exp_f32 v204, v82
	v_exp_f32 v207, v83
	s_waitcnt lgkmcnt(4)
	v_mfma_f32_32x32x16_bf16 v[34:49], v[118:121], v[134:137], v[34:49]
	ds_read_b64_tr_b16 v[100:101], v225 offset:39936
	ds_read_b64_tr_b16 v[102:103], v225 offset:40448
	v_exp_f32 v216, v84
	v_exp_f32 v218, v85
	v_exp_f32 v145, v86
	s_waitcnt lgkmcnt(4)
	v_mfma_f32_32x32x16_bf16 v[18:33], v[118:121], v[104:107], v[18:33]
	ds_read_b64_tr_b16 v[138:139], v225 offset:44032
	ds_read_b64_tr_b16 v[140:141], v225 offset:44544
	v_exp_f32 v219, v87
	v_exp_f32 v213, v88
	v_exp_f32 v214, v89
	s_waitcnt lgkmcnt(4)
	v_mfma_f32_32x32x16_bf16 v[2:17], v[114:117], v[108:111], v[2:17]
	v_add_u32_e32 v118, s38, v191
	ds_read_b64_tr_b16 v[86:87], v225 offset:48128
	ds_read_b64_tr_b16 v[88:89], v225 offset:48640
	ds_read_b128 v[82:85], v118
	v_exp_f32 v215, v90
	v_exp_f32 v217, v91
	s_waitcnt lgkmcnt(5)
	v_mfma_f32_32x32x16_bf16 v[50:65], v[114:117], v[100:103], v[50:65]
	ds_read_b128 v[130:133], v118 offset:512
	v_exp_f32 v221, v92
	v_exp_f32 v223, v93
	s_waitcnt lgkmcnt(4)
	v_mfma_f32_32x32x16_bf16 v[34:49], v[114:117], v[138:141], v[34:49]
	ds_read_b128 v[134:137], v118 offset:2048
	v_exp_f32 v222, v94
	v_exp_f32 v224, v95
	s_waitcnt lgkmcnt(3)
	v_mfma_f32_32x32x16_bf16 v[18:33], v[114:117], v[86:89], v[18:33]
	v_exp_f32 v225, v96
	v_exp_f32 v226, v97
	s_waitcnt vmcnt(3) lgkmcnt(0)
	s_barrier
	s_andn2_b64 vcc, exec, s[36:37]
	s_cbranch_vccnz .LBB0_421
	s_waitcnt lgkmcnt(0)
	v_add_u32_e32 v100, s80, v152
	ds_read_b128 v[86:89], v100 offset:96
	ds_read_b128 v[90:93], v100 offset:64
	ds_read_b128 v[94:97], v100 offset:32
	ds_read_b128 v[100:103], v100
	s_waitcnt lgkmcnt(3)
	v_pk_mul_f32 v[14:15], v[14:15], v[86:87]
	s_waitcnt lgkmcnt(2)
	v_pk_mul_f32 v[10:11], v[10:11], v[90:91]
	s_waitcnt lgkmcnt(1)
	v_pk_mul_f32 v[6:7], v[6:7], v[94:95]
	v_pk_mul_f32 v[16:17], v[16:17], v[88:89]
	v_pk_mul_f32 v[12:13], v[12:13], v[92:93]
	v_pk_mul_f32 v[8:9], v[8:9], v[96:97]
	s_waitcnt lgkmcnt(0)
	v_pk_mul_f32 v[4:5], v[4:5], v[102:103]
	v_pk_mul_f32 v[2:3], v[2:3], v[100:101]
	v_pk_mul_f32 v[62:63], v[62:63], v[86:87]
	v_pk_mul_f32 v[58:59], v[58:59], v[90:91]
	v_pk_mul_f32 v[54:55], v[54:55], v[94:95]
	v_pk_mul_f32 v[64:65], v[64:65], v[88:89]
	v_pk_mul_f32 v[60:61], v[60:61], v[92:93]
	v_pk_mul_f32 v[56:57], v[56:57], v[96:97]
	v_pk_mul_f32 v[52:53], v[52:53], v[102:103]
	v_pk_mul_f32 v[50:51], v[50:51], v[100:101]
	v_pk_mul_f32 v[46:47], v[46:47], v[86:87]
	v_pk_mul_f32 v[42:43], v[42:43], v[90:91]
	v_pk_mul_f32 v[38:39], v[38:39], v[94:95]
	v_pk_mul_f32 v[48:49], v[48:49], v[88:89]
	v_pk_mul_f32 v[44:45], v[44:45], v[92:93]
	v_pk_mul_f32 v[40:41], v[40:41], v[96:97]
	v_pk_mul_f32 v[36:37], v[36:37], v[102:103]
	v_pk_mul_f32 v[34:35], v[34:35], v[100:101]
	v_pk_mul_f32 v[30:31], v[30:31], v[86:87]
	v_pk_mul_f32 v[26:27], v[26:27], v[90:91]
	v_pk_mul_f32 v[22:23], v[22:23], v[94:95]
	v_pk_mul_f32 v[32:33], v[32:33], v[88:89]
	v_pk_mul_f32 v[28:29], v[28:29], v[92:93]
	v_pk_mul_f32 v[24:25], v[24:25], v[96:97]
	v_pk_mul_f32 v[20:21], v[20:21], v[102:103]
	v_pk_mul_f32 v[18:19], v[18:19], v[100:101]

.LBB0_432:
	ds_read_b128 v[228:231], v118 offset:2560
	v_add_u32_e32 v205, s0, v192
	v_add_f32_e32 v86, v98, v99
	v_cvt_pk_bf16_f32 v126, v98, v99
	s_waitcnt lgkmcnt(1)
	v_mfma_f32_32x32x16_bf16 v[98:113], v[82:85], v[244:247], v[66:81]
	v_add_f32_e32 v86, v86, v127
	v_add_f32_e32 v86, v86, v206
	v_add_f32_e32 v86, v86, v142
	v_add_f32_e32 v86, v86, v144
	v_cvt_pk_bf16_f32 v127, v127, v206
	ds_read_b128 v[236:239], v118 offset:4096
	v_add_f32_e32 v82, v210, v86
	v_add_f32_e32 v82, v212, v82
	v_add_f32_e32 v82, v143, v82
	v_add_f32_e32 v114, v122, v82
	v_mfma_f32_32x32x16_bf16 v[82:97], v[130:133], v[244:247], v[66:81]
	v_cvt_pk_bf16_f32 v128, v142, v144
	v_cvt_pk_bf16_f32 v129, v210, v212
	ds_read_b128 v[130:133], v118 offset:4608
	s_waitcnt lgkmcnt(2)
	v_mfma_f32_32x32x16_bf16 v[98:113], v[134:137], v[248:251], v[98:113]
	v_add_f32_e32 v114, v123, v114
	v_add_f32_e32 v114, v209, v114
	v_add_f32_e32 v114, v208, v114
	v_add_f32_e32 v114, v211, v114
	v_cvt_pk_bf16_f32 v122, v143, v122
	v_cvt_pk_bf16_f32 v123, v123, v209
	ds_read_b128 v[134:137], v118 offset:6144
	v_mfma_f32_32x32x16_bf16 v[82:97], v[228:231], v[248:251], v[82:97]
	v_add_f32_e32 v114, v203, v114
	v_add_f32_e32 v114, v220, v114
	v_add_f32_e32 v114, v204, v114
	v_add_f32_e32 v114, v207, v114
	v_cvt_pk_bf16_f32 v124, v208, v211
	v_cvt_pk_bf16_f32 v125, v203, v220
	ds_read_b128 v[208:211], v118 offset:6656
	ds_read_b128 v[228:231], v201 offset:3072
	s_waitcnt lgkmcnt(3)
	v_mfma_f32_32x32x16_bf16 v[98:113], v[236:239], v[252:255], v[98:113]
	v_add_f32_e32 v114, v216, v114
	v_add_f32_e32 v114, v218, v114
	v_add_f32_e32 v114, v145, v114
	v_add_f32_e32 v114, v219, v114
	v_cvt_pk_bf16_f32 v118, v204, v207
	v_cvt_pk_bf16_f32 v119, v216, v218
	ds_read_b64_tr_b16 v[232:233], v205 offset:32768
	ds_read_b64_tr_b16 v[234:235], v205 offset:33280
	v_mfma_f32_32x32x16_bf16 v[82:97], v[130:133], v[252:255], v[82:97]
	v_add_f32_e32 v114, v213, v114
	v_add_f32_e32 v114, v214, v114
	v_add_f32_e32 v114, v215, v114
	v_add_f32_e32 v114, v217, v114
	v_cvt_pk_bf16_f32 v120, v145, v219
	v_cvt_pk_bf16_f32 v121, v213, v214
	ds_read_b64_tr_b16 v[138:139], v205 offset:36864
	ds_read_b64_tr_b16 v[140:141], v205 offset:37376
	s_waitcnt lgkmcnt(4)
	v_mfma_f32_32x32x16_bf16 v[98:113], v[134:137], v[228:231], v[98:113]
	v_add_f32_e32 v114, v221, v114
	v_add_f32_e32 v114, v223, v114
	v_add_f32_e32 v114, v222, v114
	v_add_f32_e32 v130, v224, v114
	v_cvt_pk_bf16_f32 v114, v215, v217
	v_cvt_pk_bf16_f32 v115, v221, v223
	ds_read_b64_tr_b16 v[142:143], v205 offset:40960
	ds_read_b64_tr_b16 v[144:145], v205 offset:41472
	v_mfma_f32_32x32x16_bf16 v[82:97], v[208:211], v[228:231], v[82:97]
	v_add_f32_e32 v116, v225, v130
	v_add_f32_e32 v130, v226, v116
	v_cvt_pk_bf16_f32 v116, v222, v224
	v_cvt_pk_bf16_f32 v117, v225, v226
	s_waitcnt lgkmcnt(4)
	v_mfma_f32_32x32x16_bf16 v[2:17], v[126:129], v[232:235], v[2:17]
	ds_read_b64_tr_b16 v[134:135], v205 offset:45056
	ds_read_b64_tr_b16 v[136:137], v205 offset:45568
	s_cmp_lt_i32 s88, s3
	s_cselect_b64 s[28:29], -1, 0
	s_cmp_ge_i32 s88, s3
	s_cselect_b64 s[36:37], -1, 0
	s_and_b64 vcc, exec, s[36:37]
	s_cbranch_vccnz .LBB0_442
	s_lshl_b32 s0, s88, 8
	s_add_i32 s0, s0, s76
	s_cmpk_gt_i32 s0, 0x3ff
	s_cbranch_scc0 .LBB0_436
	s_lshl_b32 s82, s0, 6
	s_cmpk_gt_u32 s0, 0x13ff
	s_cbranch_scc0 .LBB0_437
	s_lshl_b32 s38, s0, 1
	s_add_i32 s38, s38, 0x7fffd800
	s_and_b32 s52, s38, 0x7fffffc0
	s_and_b32 s53, s82, 0x7c0
	s_mov_b64 s[38:39], s[64:65]
	s_mov_b32 s73, 11
	s_cbranch_execz .LBB0_438
	s_branch .LBB0_439

.LBB0_443:
	s_addk_i32 s30, 0x6000
	s_and_b32 s30, s30, 0x6000
	s_waitcnt lgkmcnt(4)
	v_mfma_f32_32x32x16_bf16 v[2:17], v[122:125], v[130:133], v[2:17]
	ds_read_b64_tr_b16 v[134:135], v205 offset:46080
	ds_read_b64_tr_b16 v[136:137], v205 offset:46592
	v_exp_f32 v98, v98
	v_exp_f32 v99, v99
	v_exp_f32 v127, v100
	s_waitcnt lgkmcnt(4)
	v_mfma_f32_32x32x16_bf16 v[50:65], v[122:125], v[138:141], v[50:65]
	ds_read_b64_tr_b16 v[130:131], v205 offset:34816
	ds_read_b64_tr_b16 v[132:133], v205 offset:35328
	v_exp_f32 v223, v101
	v_exp_f32 v217, v102
	v_exp_f32 v219, v103
	s_waitcnt lgkmcnt(4)
	v_mfma_f32_32x32x16_bf16 v[34:49], v[122:125], v[142:145], v[34:49]
	ds_read_b64_tr_b16 v[100:101], v205 offset:38912
	ds_read_b64_tr_b16 v[102:103], v205 offset:39424
	v_exp_f32 v222, v104
	v_exp_f32 v224, v105
	v_exp_f32 v214, v106
	s_waitcnt lgkmcnt(4)
	v_mfma_f32_32x32x16_bf16 v[18:33], v[122:125], v[134:137], v[18:33]
	ds_read_b64_tr_b16 v[138:139], v205 offset:43008
	ds_read_b64_tr_b16 v[140:141], v205 offset:43520
	v_exp_f32 v122, v107
	v_exp_f32 v123, v108
	v_exp_f32 v220, v109
	s_waitcnt lgkmcnt(4)
	v_mfma_f32_32x32x16_bf16 v[2:17], v[118:121], v[130:133], v[2:17]
	ds_read_b64_tr_b16 v[104:105], v205 offset:47104
	ds_read_b64_tr_b16 v[106:107], v205 offset:47616
	v_exp_f32 v216, v110
	v_exp_f32 v218, v111
	v_exp_f32 v215, v112
	s_waitcnt lgkmcnt(4)
	v_mfma_f32_32x32x16_bf16 v[50:65], v[118:121], v[100:103], v[50:65]
	ds_read_b64_tr_b16 v[108:109], v205 offset:35840
	ds_read_b64_tr_b16 v[110:111], v205 offset:36352
	v_exp_f32 v221, v113
	v_exp_f32 v203, v82
	v_exp_f32 v206, v83
	s_waitcnt lgkmcnt(4)
	v_mfma_f32_32x32x16_bf16 v[34:49], v[118:121], v[138:141], v[34:49]
	ds_read_b64_tr_b16 v[100:101], v205 offset:39936
	ds_read_b64_tr_b16 v[102:103], v205 offset:40448
	v_exp_f32 v212, v84
	v_exp_f32 v213, v85
	v_exp_f32 v142, v86
	s_waitcnt lgkmcnt(4)
	v_mfma_f32_32x32x16_bf16 v[18:33], v[118:121], v[104:107], v[18:33]
	ds_read_b64_tr_b16 v[138:139], v205 offset:44032
	ds_read_b64_tr_b16 v[140:141], v205 offset:44544
	v_exp_f32 v209, v87
	v_exp_f32 v204, v88
	v_exp_f32 v207, v89
	s_waitcnt lgkmcnt(4)
	v_mfma_f32_32x32x16_bf16 v[2:17], v[114:117], v[108:111], v[2:17]
	v_add_u32_e32 v104, s30, v191
	ds_read_b64_tr_b16 v[86:87], v205 offset:48128
	ds_read_b64_tr_b16 v[88:89], v205 offset:48640
	ds_read_b128 v[82:85], v104
	v_exp_f32 v144, v90
	v_exp_f32 v202, v91
	s_waitcnt lgkmcnt(5)
	v_mfma_f32_32x32x16_bf16 v[50:65], v[114:117], v[100:103], v[50:65]
	ds_read_b128 v[134:137], v104 offset:512
	v_exp_f32 v205, v92
	v_exp_f32 v210, v93
	s_waitcnt lgkmcnt(4)
	v_mfma_f32_32x32x16_bf16 v[34:49], v[114:117], v[138:141], v[34:49]
	ds_read_b128 v[130:133], v104 offset:2048
	v_exp_f32 v143, v94
	v_exp_f32 v145, v95
	s_waitcnt lgkmcnt(3)
	v_mfma_f32_32x32x16_bf16 v[18:33], v[114:117], v[86:89], v[18:33]
	v_exp_f32 v208, v96
	v_exp_f32 v211, v97
	s_mov_b64 s[30:31], -1
	s_and_b64 vcc, exec, s[36:37]
	s_cbranch_vccnz .LBB0_449
	s_andn2_b64 vcc, exec, s[30:31]
	s_cbranch_vccz .LBB0_450

.LBB0_457:
	ds_read_b128 v[176:179], v191 offset:10752
	v_add_f32_e32 v86, v98, v99
	v_cvt_pk_bf16_f32 v126, v98, v99
	s_waitcnt lgkmcnt(1)
	v_mfma_f32_32x32x16_bf16 v[98:113], v[82:85], v[244:247], v[66:81]
	v_add_f32_e32 v86, v127, v86
	v_add_f32_e32 v86, v86, v223
	v_add_f32_e32 v86, v217, v86
	v_add_f32_e32 v86, v219, v86
	v_cvt_pk_bf16_f32 v127, v127, v223
	ds_read_b128 v[230:233], v191 offset:12288
	v_add_f32_e32 v82, v222, v86
	v_add_f32_e32 v82, v224, v82
	v_add_f32_e32 v82, v214, v82
	v_add_f32_e32 v114, v122, v82
	v_mfma_f32_32x32x16_bf16 v[82:97], v[134:137], v[244:247], v[66:81]
	v_cvt_pk_bf16_f32 v128, v217, v219
	v_cvt_pk_bf16_f32 v129, v222, v224
	ds_read_b128 v[134:137], v191 offset:12800
	s_waitcnt lgkmcnt(2)
	v_mfma_f32_32x32x16_bf16 v[98:113], v[130:133], v[248:251], v[98:113]
	v_add_f32_e32 v114, v123, v114
	v_add_f32_e32 v114, v220, v114
	v_add_f32_e32 v114, v216, v114
	v_add_f32_e32 v114, v218, v114
	v_cvt_pk_bf16_f32 v122, v214, v122
	v_cvt_pk_bf16_f32 v123, v123, v220
	ds_read_b128 v[130:133], v191 offset:14336
	v_mfma_f32_32x32x16_bf16 v[82:97], v[176:179], v[248:251], v[82:97]
	v_add_f32_e32 v114, v215, v114
	v_add_f32_e32 v114, v221, v114
	v_add_f32_e32 v114, v203, v114
	v_add_f32_e32 v114, v206, v114
	v_cvt_pk_bf16_f32 v124, v216, v218
	v_cvt_pk_bf16_f32 v125, v215, v221
	ds_read_b128 v[176:179], v191 offset:14848
	ds_read_b128 v[214:217], v201 offset:3072
	s_waitcnt lgkmcnt(3)
	v_mfma_f32_32x32x16_bf16 v[98:113], v[230:233], v[252:255], v[98:113]
	v_add_f32_e32 v114, v212, v114
	v_add_f32_e32 v114, v213, v114
	v_add_f32_e32 v114, v142, v114
	v_add_f32_e32 v114, v209, v114
	v_cvt_pk_bf16_f32 v118, v203, v206
	v_cvt_pk_bf16_f32 v119, v212, v213
	ds_read_b64_tr_b16 v[218:219], v192 offset:32768
	ds_read_b64_tr_b16 v[220:221], v192 offset:33280
	v_mfma_f32_32x32x16_bf16 v[82:97], v[134:137], v[252:255], v[82:97]
	v_add_f32_e32 v114, v204, v114
	v_add_f32_e32 v114, v207, v114
	v_add_f32_e32 v114, v144, v114
	v_add_f32_e32 v114, v202, v114
	v_cvt_pk_bf16_f32 v120, v142, v209
	v_cvt_pk_bf16_f32 v121, v204, v207
	ds_read_b64_tr_b16 v[134:135], v192 offset:36864
	ds_read_b64_tr_b16 v[136:137], v192 offset:37376
	s_waitcnt lgkmcnt(4)
	v_mfma_f32_32x32x16_bf16 v[98:113], v[130:133], v[214:217], v[98:113]
	v_add_f32_e32 v114, v205, v114
	v_add_f32_e32 v114, v210, v114
	v_add_f32_e32 v114, v143, v114
	v_add_f32_e32 v130, v145, v114
	v_cvt_pk_bf16_f32 v114, v144, v202
	v_cvt_pk_bf16_f32 v115, v205, v210
	ds_read_b64_tr_b16 v[138:139], v192 offset:40960
	ds_read_b64_tr_b16 v[140:141], v192 offset:41472
	v_mfma_f32_32x32x16_bf16 v[82:97], v[176:179], v[214:217], v[82:97]
	v_add_f32_e32 v116, v208, v130
	v_add_f32_e32 v130, v211, v116
	v_cvt_pk_bf16_f32 v116, v143, v145
	v_cvt_pk_bf16_f32 v117, v208, v211
	s_waitcnt lgkmcnt(4)
	v_mfma_f32_32x32x16_bf16 v[2:17], v[126:129], v[218:221], v[2:17]
	ds_read_b64_tr_b16 v[176:177], v192 offset:45056
	ds_read_b64_tr_b16 v[178:179], v192 offset:45568
	v_add_f32_e32 v143, v146, v130
	s_nop 2
	v_max3_f32 v130, v98, v99, v82
	v_max3_f32 v131, v100, v101, v83
	v_max3_f32 v130, v130, v84, v85
	v_max3_f32 v142, v130, v102, v103
	v_max3_f32 v144, v131, v104, v105
	s_waitcnt lgkmcnt(4)
	v_mfma_f32_32x32x16_bf16 v[50:65], v[126:129], v[134:137], v[50:65]
	ds_read_b64_tr_b16 v[130:131], v192 offset:33792
	ds_read_b64_tr_b16 v[132:133], v192 offset:34304
	v_max3_f32 v134, v142, v86, v87
	v_max3_f32 v135, v144, v88, v89
	v_max3_f32 v142, v134, v106, v107
	v_max3_f32 v144, v135, v108, v109
	s_waitcnt lgkmcnt(4)
	v_mfma_f32_32x32x16_bf16 v[34:49], v[126:129], v[138:141], v[34:49]
	s_cmp_lg_u32 0, -1
	s_cselect_b32 s0, 0, 0
	ds_read_b64_tr_b16 v[134:135], v192 offset:37888
	ds_read_b64_tr_b16 v[136:137], v192 offset:38400
	s_add_i32 s0, s0, s96
	s_add_i32 s2, s0, 0x10000
	s_mov_b32 m0, s2
	s_nop 0
	global_load_lds_dwordx4 v[164:165], off
	s_add_i32 s0, s0, 0x10400
	s_mov_b32 m0, s0
	s_nop 0
	global_load_lds_dwordx4 v[166:167], off
	v_max3_f32 v138, v142, v90, v91
	v_max3_f32 v139, v144, v92, v93
	v_max3_f32 v142, v138, v110, v111
	v_max3_f32 v144, v139, v112, v113
	s_waitcnt lgkmcnt(4)
	v_mfma_f32_32x32x16_bf16 v[18:33], v[126:129], v[176:179], v[18:33]
	v_max3_f32 v126, v142, v94, v95
	v_max3_f32 v127, v144, v96, v97
	ds_read_b64_tr_b16 v[138:139], v192 offset:41984
	ds_read_b64_tr_b16 v[140:141], v192 offset:42496
	v_max_f32 v126, v126, v127
	s_nop 0
	v_mov_b32_e32 v127, v126
	s_nop 1
	v_permlane32_swap_b32_e32 v126, v127
	v_max_f32 v126, v126, v127
	s_nop 0
	v_cmp_lt_f32_e32 vcc, s49, v126
	s_cmp_lg_u64 vcc, 0
	s_cselect_b64 s[30:31], -1, 0
	s_cbranch_vccnz .LBB0_497
; #define WAIT_BAR(N) asm volatile("s_waitcnt vmcnt(" #N ") lgkmcnt(0)\n\ts_barrier" ::: "memory")
; #define SJ_DRAIN() do { if (sjp) { att::side_drain(SJ, sj, tid, shm); ++sj; sjp = false; } } while (0)
; #define SJ_WAIT_BAR() do { if (sji) { WAIT_BAR(5); sji = false; } else { WAIT_BAR(3); } } while (0)
; #define RESC() do { if (resc) { asm volatile("s_waitcnt lgkmcnt(0)" ::: "memory"); \
;       _Pragma("unroll") for (int d_ = 0; d_ < 4; ++d_) _Pragma("unroll") for (int r = 0; r < 16; ++r) o[d_][r] *= wsf[crow(r, hi)]; } } while (0)
; #define ROT() do { sl_prev = sl_cur; sl_cur = sl_next; sl_next = (sl_next == 2 * VSLOT) ? 0 : sl_next + VSLOT; } while (0)
; template <int THRL> ...
;     ...
;     int t = 1;
;     for (; t + 4 < NT; t += 2) {
;       STEP(pB0, pB1, pA0, pA1, t, true, true, true, false);                    WAIT_BAR(3);   RESC(); ROT();
;       SJ_DRAIN(); STEP(pA0, pA1, pB0, pB1, t + 1, true, true, true, true);     SJ_WAIT_BAR(); RESC(); ROT();
;     }
;     STEP(pB0, pB1, pA0, pA1, NT - 3, false, true, true, false);              WAIT_BAR(2); RESC(); ROT();
.LBB0_458:
	s_waitcnt lgkmcnt(4)
	v_mfma_f32_32x32x16_bf16 v[2:17], v[122:125], v[130:133], v[2:17]
	ds_read_b64_tr_b16 v[206:207], v192 offset:46080
	ds_read_b64_tr_b16 v[208:209], v192 offset:46592
	v_exp_f32 v98, v98
	v_exp_f32 v99, v99
	v_exp_f32 v127, v100
	s_waitcnt lgkmcnt(4)
	v_mfma_f32_32x32x16_bf16 v[50:65], v[122:125], v[134:137], v[50:65]
	ds_read_b64_tr_b16 v[130:131], v192 offset:34816
	ds_read_b64_tr_b16 v[132:133], v192 offset:35328
	v_exp_f32 v177, v101
	v_exp_f32 v144, v102
	v_exp_f32 v176, v103
	s_waitcnt lgkmcnt(4)
	v_mfma_f32_32x32x16_bf16 v[34:49], v[122:125], v[138:141], v[34:49]
	ds_read_b64_tr_b16 v[100:101], v192 offset:38912
	ds_read_b64_tr_b16 v[102:103], v192 offset:39424
	v_exp_f32 v181, v104
	v_exp_f32 v205, v105
	v_exp_f32 v145, v106
	s_waitcnt lgkmcnt(4)
	v_mfma_f32_32x32x16_bf16 v[18:33], v[122:125], v[206:209], v[18:33]
	ds_read_b64_tr_b16 v[134:135], v192 offset:43008
	ds_read_b64_tr_b16 v[136:137], v192 offset:43520
	v_exp_f32 v122, v107
	v_exp_f32 v123, v108
	v_exp_f32 v202, v109
	s_waitcnt lgkmcnt(4)
	v_mfma_f32_32x32x16_bf16 v[2:17], v[118:121], v[130:133], v[2:17]
	ds_read_b64_tr_b16 v[104:105], v192 offset:47104
	ds_read_b64_tr_b16 v[106:107], v192 offset:47616
	v_exp_f32 v203, v110
	v_exp_f32 v206, v111
	v_exp_f32 v179, v112
	s_waitcnt lgkmcnt(4)
	v_mfma_f32_32x32x16_bf16 v[50:65], v[118:121], v[100:103], v[50:65]
	ds_read_b64_tr_b16 v[108:109], v192 offset:35840
	ds_read_b64_tr_b16 v[110:111], v192 offset:36352
	v_exp_f32 v212, v113
	v_exp_f32 v180, v82
	v_exp_f32 v204, v83
	s_waitcnt lgkmcnt(4)
	v_mfma_f32_32x32x16_bf16 v[34:49], v[118:121], v[134:137], v[34:49]
	ds_read_b64_tr_b16 v[100:101], v192 offset:39936
	ds_read_b64_tr_b16 v[102:103], v192 offset:40448
	v_exp_f32 v208, v84
	v_exp_f32 v210, v85
	v_exp_f32 v178, v86
	s_waitcnt lgkmcnt(4)
	v_mfma_f32_32x32x16_bf16 v[18:33], v[118:121], v[104:107], v[18:33]
	ds_read_b64_tr_b16 v[138:139], v192 offset:44032
	ds_read_b64_tr_b16 v[140:141], v192 offset:44544
	v_exp_f32 v211, v87
	v_exp_f32 v207, v88
	v_exp_f32 v209, v89
	s_waitcnt lgkmcnt(4)
	v_mfma_f32_32x32x16_bf16 v[2:17], v[114:117], v[108:111], v[2:17]
	ds_read_b64_tr_b16 v[86:87], v192 offset:48128
	ds_read_b64_tr_b16 v[88:89], v192 offset:48640
	ds_read_b128 v[82:85], v191 offset:16384
	v_exp_f32 v213, v90
	v_exp_f32 v214, v91
	s_waitcnt lgkmcnt(5)
	v_mfma_f32_32x32x16_bf16 v[50:65], v[114:117], v[100:103], v[50:65]
	ds_read_b128 v[134:137], v191 offset:16896
	v_exp_f32 v215, v92
	v_exp_f32 v216, v93
	s_waitcnt lgkmcnt(4)
	v_mfma_f32_32x32x16_bf16 v[34:49], v[114:117], v[138:141], v[34:49]
	ds_read_b128 v[130:133], v191 offset:18432
	v_exp_f32 v217, v94
	v_exp_f32 v218, v95
	s_waitcnt lgkmcnt(3)
	v_mfma_f32_32x32x16_bf16 v[18:33], v[114:117], v[86:89], v[18:33]
	v_exp_f32 v219, v96
	v_exp_f32 v220, v97
	s_waitcnt vmcnt(2) lgkmcnt(0)
	s_barrier
	s_andn2_b64 vcc, exec, s[30:31]
	v_add_u32_e32 v142, s80, v152
	s_cbranch_vccnz .LBB0_460
	s_waitcnt lgkmcnt(0)
	ds_read_b128 v[86:89], v142 offset:96
	ds_read_b128 v[90:93], v142 offset:64
	ds_read_b128 v[94:97], v142 offset:32
	ds_read_b128 v[100:103], v142
	s_waitcnt lgkmcnt(3)
	v_pk_mul_f32 v[14:15], v[14:15], v[86:87]
	s_waitcnt lgkmcnt(2)
	v_pk_mul_f32 v[10:11], v[10:11], v[90:91]
	s_waitcnt lgkmcnt(1)
	v_pk_mul_f32 v[6:7], v[6:7], v[94:95]
	v_pk_mul_f32 v[16:17], v[16:17], v[88:89]
	v_pk_mul_f32 v[12:13], v[12:13], v[92:93]
	v_pk_mul_f32 v[8:9], v[8:9], v[96:97]
	s_waitcnt lgkmcnt(0)
	v_pk_mul_f32 v[4:5], v[4:5], v[102:103]
	v_pk_mul_f32 v[2:3], v[2:3], v[100:101]
	v_pk_mul_f32 v[62:63], v[62:63], v[86:87]
	v_pk_mul_f32 v[58:59], v[58:59], v[90:91]
	v_pk_mul_f32 v[54:55], v[54:55], v[94:95]
	v_pk_mul_f32 v[64:65], v[64:65], v[88:89]
	v_pk_mul_f32 v[60:61], v[60:61], v[92:93]
	v_pk_mul_f32 v[56:57], v[56:57], v[96:97]
	v_pk_mul_f32 v[52:53], v[52:53], v[102:103]
	v_pk_mul_f32 v[50:51], v[50:51], v[100:101]
	v_pk_mul_f32 v[46:47], v[46:47], v[86:87]
	v_pk_mul_f32 v[42:43], v[42:43], v[90:91]
	v_pk_mul_f32 v[38:39], v[38:39], v[94:95]
	v_pk_mul_f32 v[48:49], v[48:49], v[88:89]
	v_pk_mul_f32 v[44:45], v[44:45], v[92:93]
	v_pk_mul_f32 v[40:41], v[40:41], v[96:97]
	v_pk_mul_f32 v[36:37], v[36:37], v[102:103]
	v_pk_mul_f32 v[34:35], v[34:35], v[100:101]
	v_pk_mul_f32 v[30:31], v[30:31], v[86:87]
	v_pk_mul_f32 v[26:27], v[26:27], v[90:91]
	v_pk_mul_f32 v[22:23], v[22:23], v[94:95]
	v_pk_mul_f32 v[32:33], v[32:33], v[88:89]
	v_pk_mul_f32 v[28:29], v[28:29], v[92:93]
	v_pk_mul_f32 v[24:25], v[24:25], v[96:97]
	v_pk_mul_f32 v[20:21], v[20:21], v[102:103]
	v_pk_mul_f32 v[18:19], v[18:19], v[100:101]

.LBB0_471:
	ds_read_b128 v[222:225], v191 offset:18944
	v_add_f32_e32 v86, v98, v99
	v_cvt_pk_bf16_f32 v126, v98, v99
	s_waitcnt lgkmcnt(1)
	v_mfma_f32_32x32x16_bf16 v[98:113], v[82:85], v[244:247], v[66:81]
	v_add_f32_e32 v86, v86, v127
	v_add_f32_e32 v86, v86, v177
	v_add_f32_e32 v86, v86, v144
	v_add_f32_e32 v86, v86, v176
	v_cvt_pk_bf16_f32 v127, v127, v177
	ds_read_b128 v[230:233], v191 offset:20480
	v_add_f32_e32 v82, v181, v86
	v_add_f32_e32 v82, v205, v82
	v_add_f32_e32 v82, v145, v82
	v_add_f32_e32 v114, v122, v82
	v_mfma_f32_32x32x16_bf16 v[82:97], v[134:137], v[244:247], v[66:81]
	v_cvt_pk_bf16_f32 v128, v144, v176
	v_cvt_pk_bf16_f32 v129, v181, v205
	ds_read_b128 v[134:137], v191 offset:20992
	s_waitcnt lgkmcnt(2)
	v_mfma_f32_32x32x16_bf16 v[98:113], v[130:133], v[248:251], v[98:113]
	v_add_f32_e32 v114, v123, v114
	v_add_f32_e32 v114, v202, v114
	v_add_f32_e32 v114, v203, v114
	v_add_f32_e32 v114, v206, v114
	v_cvt_pk_bf16_f32 v122, v145, v122
	v_cvt_pk_bf16_f32 v123, v123, v202
	ds_read_b128 v[130:133], v191 offset:22528
	v_mfma_f32_32x32x16_bf16 v[82:97], v[222:225], v[248:251], v[82:97]
	v_add_f32_e32 v114, v179, v114
	v_add_f32_e32 v114, v212, v114
	v_add_f32_e32 v114, v180, v114
	v_add_f32_e32 v114, v204, v114
	v_cvt_pk_bf16_f32 v124, v203, v206
	v_cvt_pk_bf16_f32 v125, v179, v212
	ds_read_b128 v[222:225], v191 offset:23040
	ds_read_b128 v[226:229], v201 offset:3072
	s_waitcnt lgkmcnt(3)
	v_mfma_f32_32x32x16_bf16 v[98:113], v[230:233], v[252:255], v[98:113]
	v_add_f32_e32 v114, v208, v114
	v_add_f32_e32 v114, v210, v114
	v_add_f32_e32 v114, v178, v114
	v_add_f32_e32 v114, v211, v114
	v_cvt_pk_bf16_f32 v118, v180, v204
	v_cvt_pk_bf16_f32 v119, v208, v210
	ds_read_b64_tr_b16 v[202:203], v192 offset:49152
	ds_read_b64_tr_b16 v[204:205], v192 offset:49664
	v_mfma_f32_32x32x16_bf16 v[82:97], v[134:137], v[252:255], v[82:97]
	v_add_f32_e32 v114, v207, v114
	v_add_f32_e32 v114, v209, v114
	v_add_f32_e32 v114, v213, v114
	v_add_f32_e32 v114, v214, v114
	v_cvt_pk_bf16_f32 v120, v178, v211
	v_cvt_pk_bf16_f32 v121, v207, v209
	ds_read_b64_tr_b16 v[134:135], v192 offset:53248
	ds_read_b64_tr_b16 v[136:137], v192 offset:53760
	s_waitcnt lgkmcnt(4)
	v_mfma_f32_32x32x16_bf16 v[98:113], v[130:133], v[226:229], v[98:113]
	v_add_f32_e32 v114, v215, v114
	v_add_f32_e32 v114, v216, v114
	v_add_f32_e32 v114, v217, v114
	v_add_f32_e32 v144, v218, v114
	v_cvt_pk_bf16_f32 v114, v213, v214
	v_cvt_pk_bf16_f32 v115, v215, v216
	ds_read_b64_tr_b16 v[138:139], v192 offset:57344
	ds_read_b64_tr_b16 v[140:141], v192 offset:57856
	v_mfma_f32_32x32x16_bf16 v[82:97], v[222:225], v[226:229], v[82:97]
	v_add_f32_e32 v116, v219, v144
	v_add_f32_e32 v130, v220, v116
	v_cvt_pk_bf16_f32 v116, v217, v218
	v_cvt_pk_bf16_f32 v117, v219, v220
	s_waitcnt lgkmcnt(4)
	v_mfma_f32_32x32x16_bf16 v[2:17], v[126:129], v[202:205], v[2:17]
	ds_read_b64_tr_b16 v[176:177], v192 offset:61440
	ds_read_b64_tr_b16 v[178:179], v192 offset:61952
	v_add_f32_e32 v143, v143, v130
	s_nop 2
	v_max3_f32 v130, v98, v99, v82
	v_max3_f32 v131, v100, v101, v83
	v_max3_f32 v130, v130, v84, v85
	v_max3_f32 v144, v130, v102, v103
	v_max3_f32 v145, v131, v104, v105
	s_waitcnt lgkmcnt(4)
	v_mfma_f32_32x32x16_bf16 v[50:65], v[126:129], v[134:137], v[50:65]
	ds_read_b64_tr_b16 v[130:131], v192 offset:50176
	ds_read_b64_tr_b16 v[132:133], v192 offset:50688
	v_max3_f32 v144, v144, v86, v87
	v_max3_f32 v145, v145, v88, v89
	v_max3_f32 v144, v144, v106, v107
	v_max3_f32 v145, v145, v108, v109
	s_waitcnt lgkmcnt(4)
	v_mfma_f32_32x32x16_bf16 v[34:49], v[126:129], v[138:141], v[34:49]
	ds_read_b64_tr_b16 v[134:135], v192 offset:54272
	ds_read_b64_tr_b16 v[136:137], v192 offset:54784
	s_mov_b32 m0, s97
	s_nop 0
	global_load_lds_dwordx4 v[168:169], off
	s_add_i32 s0, s97, 0x400
	s_mov_b32 m0, s0
	s_nop 0
	global_load_lds_dwordx4 v[170:171], off
	v_max3_f32 v138, v144, v90, v91
	v_max3_f32 v139, v145, v92, v93
	v_max3_f32 v144, v138, v110, v111
	v_max3_f32 v145, v139, v112, v113
	s_waitcnt lgkmcnt(4)
	v_mfma_f32_32x32x16_bf16 v[18:33], v[126:129], v[176:179], v[18:33]
	v_max3_f32 v126, v144, v94, v95
	v_max3_f32 v127, v145, v96, v97
	ds_read_b64_tr_b16 v[138:139], v192 offset:58368
	ds_read_b64_tr_b16 v[140:141], v192 offset:58880
	v_max_f32 v126, v126, v127
	s_nop 0
	v_mov_b32_e32 v127, v126
	s_nop 1
	v_permlane32_swap_b32_e32 v126, v127
	v_max_f32 v126, v126, v127
	s_nop 0
	v_cmp_lt_f32_e32 vcc, s49, v126
	s_cmp_lg_u64 vcc, 0
	s_cselect_b64 s[28:29], -1, 0
	s_cbranch_vccnz .LBB0_500
; #define WAIT_BAR(N) asm volatile("s_waitcnt vmcnt(" #N ") lgkmcnt(0)\n\ts_barrier" ::: "memory")
; #define SJ_DRAIN() do { if (sjp) { att::side_drain(SJ, sj, tid, shm); ++sj; sjp = false; } } while (0)
; #define SJ_WAIT_BAR() do { if (sji) { WAIT_BAR(5); sji = false; } else { WAIT_BAR(3); } } while (0)
; #define RESC() do { if (resc) { asm volatile("s_waitcnt lgkmcnt(0)" ::: "memory"); \
;       _Pragma("unroll") for (int d_ = 0; d_ < 4; ++d_) _Pragma("unroll") for (int r = 0; r < 16; ++r) o[d_][r] *= wsf[crow(r, hi)]; } } while (0)
; #define ROT() do { sl_prev = sl_cur; sl_cur = sl_next; sl_next = (sl_next == 2 * VSLOT) ? 0 : sl_next + VSLOT; } while (0)
; template <int THRL> ...
;     ...
;     int t = 1;
;     for (; t + 4 < NT; t += 2) {
;       STEP(pB0, pB1, pA0, pA1, t, true, true, true, false);                    WAIT_BAR(3);   RESC(); ROT();
;       SJ_DRAIN(); STEP(pA0, pA1, pB0, pB1, t + 1, true, true, true, true);     SJ_WAIT_BAR(); RESC(); ROT();
;     }
;     STEP(pB0, pB1, pA0, pA1, NT - 3, false, true, true, false);              WAIT_BAR(2); RESC(); ROT();
;     SJ_DRAIN(); STEP(pA0, pA1, pB0, pB1, NT - 2, false, true, true, false);  WAIT_BAR(0); RESC(); ROT();
.LBB0_472:
	s_waitcnt lgkmcnt(4)
	v_mfma_f32_32x32x16_bf16 v[2:17], v[122:125], v[130:133], v[2:17]
	ds_read_b64_tr_b16 v[176:177], v192 offset:62464
	ds_read_b64_tr_b16 v[178:179], v192 offset:62976
	v_exp_f32 v126, v98
	v_exp_f32 v131, v99
	v_exp_f32 v127, v100
	s_waitcnt lgkmcnt(4)
	v_mfma_f32_32x32x16_bf16 v[50:65], v[122:125], v[134:137], v[50:65]
	ds_read_b64_tr_b16 v[202:203], v192 offset:51200
	ds_read_b64_tr_b16 v[204:205], v192 offset:51712
	v_exp_f32 v145, v101
	v_exp_f32 v132, v102
	v_exp_f32 v133, v103
	s_waitcnt lgkmcnt(4)
	v_mfma_f32_32x32x16_bf16 v[34:49], v[122:125], v[138:141], v[34:49]
	ds_read_b64_tr_b16 v[98:99], v192 offset:55296
	ds_read_b64_tr_b16 v[100:101], v192 offset:55808
	v_exp_f32 v137, v104
	v_exp_f32 v141, v105
	v_exp_f32 v130, v106
	s_waitcnt lgkmcnt(4)
	v_mfma_f32_32x32x16_bf16 v[18:33], v[122:125], v[176:179], v[18:33]
	ds_read_b64_tr_b16 v[102:103], v192 offset:59392
	ds_read_b64_tr_b16 v[104:105], v192 offset:59904
	v_exp_f32 v122, v107
	v_exp_f32 v123, v108
	v_exp_f32 v138, v109
	s_waitcnt lgkmcnt(4)
	v_mfma_f32_32x32x16_bf16 v[2:17], v[118:121], v[202:205], v[2:17]
	ds_read_b64_tr_b16 v[106:107], v192 offset:63488
	ds_read_b64_tr_b16 v[108:109], v192 offset:64000
	v_exp_f32 v139, v110
	v_exp_f32 v144, v111
	v_exp_f32 v135, v112
	s_waitcnt lgkmcnt(4)
	v_mfma_f32_32x32x16_bf16 v[50:65], v[118:121], v[98:101], v[50:65]
	ds_read_b64_tr_b16 v[202:203], v192 offset:52224
	ds_read_b64_tr_b16 v[204:205], v192 offset:52736
	v_exp_f32 v180, v113
	v_exp_f32 v136, v82
	v_exp_f32 v140, v83
	s_waitcnt lgkmcnt(4)
	v_mfma_f32_32x32x16_bf16 v[34:49], v[118:121], v[102:105], v[34:49]
	ds_read_b64_tr_b16 v[98:99], v192 offset:56320
	ds_read_b64_tr_b16 v[100:101], v192 offset:56832
	v_exp_f32 v176, v84
	v_exp_f32 v178, v85
	v_exp_f32 v134, v86
	s_waitcnt lgkmcnt(4)
	v_mfma_f32_32x32x16_bf16 v[18:33], v[118:121], v[106:109], v[18:33]
	ds_read_b64_tr_b16 v[82:83], v192 offset:60416
	ds_read_b64_tr_b16 v[84:85], v192 offset:60928
	v_exp_f32 v179, v87
	v_exp_f32 v146, v88
	v_exp_f32 v177, v89
	s_waitcnt lgkmcnt(4)
	v_mfma_f32_32x32x16_bf16 v[2:17], v[114:117], v[202:205], v[2:17]
	ds_read_b64_tr_b16 v[86:87], v192 offset:64512
	ds_read_b64_tr_b16 v[88:89], v192 offset:65024
	ds_read_b128 v[106:109], v191 offset:24576
	v_exp_f32 v181, v90
	v_exp_f32 v202, v91
	s_waitcnt lgkmcnt(5)
	v_mfma_f32_32x32x16_bf16 v[50:65], v[114:117], v[98:101], v[50:65]
	ds_read_b128 v[102:105], v191 offset:25088
	v_exp_f32 v203, v92
	v_exp_f32 v204, v93
	s_waitcnt lgkmcnt(4)
	v_mfma_f32_32x32x16_bf16 v[34:49], v[114:117], v[82:85], v[34:49]
	ds_read_b128 v[98:101], v191 offset:26624
	v_exp_f32 v205, v94
	v_exp_f32 v206, v95
	s_waitcnt lgkmcnt(3)
	v_mfma_f32_32x32x16_bf16 v[18:33], v[114:117], v[86:89], v[18:33]
	v_exp_f32 v207, v96
	v_exp_f32 v208, v97
	s_waitcnt vmcnt(0) lgkmcnt(0)
	s_barrier
	s_andn2_b64 vcc, exec, s[28:29]
	s_cbranch_vccnz .LBB0_474
	s_waitcnt lgkmcnt(0)
	ds_read_b128 v[82:85], v142 offset:96
	ds_read_b128 v[86:89], v142 offset:64
	ds_read_b128 v[90:93], v142 offset:32
	ds_read_b128 v[94:97], v142
	s_waitcnt lgkmcnt(3)
	v_pk_mul_f32 v[14:15], v[14:15], v[82:83]
	s_waitcnt lgkmcnt(2)
	v_pk_mul_f32 v[10:11], v[10:11], v[86:87]
	s_waitcnt lgkmcnt(1)
	v_pk_mul_f32 v[6:7], v[6:7], v[90:91]
	v_pk_mul_f32 v[16:17], v[16:17], v[84:85]
	v_pk_mul_f32 v[12:13], v[12:13], v[88:89]
	v_pk_mul_f32 v[8:9], v[8:9], v[92:93]
	s_waitcnt lgkmcnt(0)
	v_pk_mul_f32 v[4:5], v[4:5], v[96:97]
	v_pk_mul_f32 v[2:3], v[2:3], v[94:95]
	v_pk_mul_f32 v[62:63], v[62:63], v[82:83]
	v_pk_mul_f32 v[58:59], v[58:59], v[86:87]
	v_pk_mul_f32 v[54:55], v[54:55], v[90:91]
	v_pk_mul_f32 v[64:65], v[64:65], v[84:85]
	v_pk_mul_f32 v[60:61], v[60:61], v[88:89]
	v_pk_mul_f32 v[56:57], v[56:57], v[92:93]
	v_pk_mul_f32 v[52:53], v[52:53], v[96:97]
	v_pk_mul_f32 v[50:51], v[50:51], v[94:95]
	v_pk_mul_f32 v[46:47], v[46:47], v[82:83]
	v_pk_mul_f32 v[42:43], v[42:43], v[86:87]
	v_pk_mul_f32 v[38:39], v[38:39], v[90:91]
	v_pk_mul_f32 v[48:49], v[48:49], v[84:85]
	v_pk_mul_f32 v[44:45], v[44:45], v[88:89]
	v_pk_mul_f32 v[40:41], v[40:41], v[92:93]
	v_pk_mul_f32 v[36:37], v[36:37], v[96:97]
	v_pk_mul_f32 v[34:35], v[34:35], v[94:95]
	v_pk_mul_f32 v[30:31], v[30:31], v[82:83]
	v_pk_mul_f32 v[26:27], v[26:27], v[86:87]
	v_pk_mul_f32 v[22:23], v[22:23], v[90:91]
	v_pk_mul_f32 v[32:33], v[32:33], v[84:85]
	v_pk_mul_f32 v[28:29], v[28:29], v[88:89]
	v_pk_mul_f32 v[24:25], v[24:25], v[92:93]
	v_pk_mul_f32 v[20:21], v[20:21], v[96:97]
	v_pk_mul_f32 v[18:19], v[18:19], v[94:95]
.LBB0_474:
	ds_read_b128 v[210:213], v191 offset:27136
	v_add_f32_e32 v82, v126, v131
	v_add_f32_e32 v82, v82, v127
	v_add_f32_e32 v82, v82, v145
	v_add_f32_e32 v82, v82, v132
	v_add_f32_e32 v114, v82, v133
	s_waitcnt lgkmcnt(1)
	v_mfma_f32_32x32x16_bf16 v[82:97], v[106:109], v[244:247], v[66:81]
	v_cvt_pk_bf16_f32 v126, v126, v131
	v_cvt_pk_bf16_f32 v127, v127, v145
	ds_read_b128 v[106:109], v191 offset:28672
	v_mfma_f32_32x32x16_bf16 v[66:81], v[102:105], v[244:247], v[66:81]
	v_add_f32_e32 v114, v137, v114
	v_add_f32_e32 v114, v141, v114
	v_add_f32_e32 v114, v130, v114
	v_add_f32_e32 v114, v122, v114
	v_cvt_pk_bf16_f32 v128, v132, v133
	v_cvt_pk_bf16_f32 v129, v137, v141
	ds_read_b128 v[102:105], v191 offset:29184
	s_waitcnt lgkmcnt(2)
	v_mfma_f32_32x32x16_bf16 v[82:97], v[98:101], v[248:251], v[82:97]
	v_add_f32_e32 v114, v123, v114
	v_add_f32_e32 v114, v138, v114
	v_add_f32_e32 v114, v139, v114
	v_add_f32_e32 v114, v144, v114
	v_cvt_pk_bf16_f32 v122, v130, v122
	v_cvt_pk_bf16_f32 v123, v123, v138
	ds_read_b128 v[98:101], v191 offset:30720
	v_mfma_f32_32x32x16_bf16 v[66:81], v[210:213], v[248:251], v[66:81]
	v_add_f32_e32 v114, v135, v114
	v_add_f32_e32 v114, v180, v114
	v_add_f32_e32 v114, v136, v114
	v_add_f32_e32 v114, v140, v114
	v_cvt_pk_bf16_f32 v124, v139, v144
	v_cvt_pk_bf16_f32 v125, v135, v180
	ds_read_b128 v[130:133], v191 offset:31232
	ds_read_b128 v[210:213], v201 offset:3072
	s_waitcnt lgkmcnt(3)
	v_mfma_f32_32x32x16_bf16 v[82:97], v[106:109], v[252:255], v[82:97]
	v_add_f32_e32 v114, v176, v114
	v_add_f32_e32 v114, v178, v114
	v_add_f32_e32 v114, v134, v114
	v_add_f32_e32 v114, v179, v114
	v_cvt_pk_bf16_f32 v118, v136, v140
	v_cvt_pk_bf16_f32 v119, v176, v178
	ds_read_b64_tr_b16 v[106:107], v193 offset:32768
	ds_read_b64_tr_b16 v[108:109], v193 offset:33280
	v_mfma_f32_32x32x16_bf16 v[66:81], v[102:105], v[252:255], v[66:81]
	v_add_f32_e32 v114, v146, v114
	v_add_f32_e32 v114, v177, v114
	v_add_f32_e32 v114, v181, v114
	v_add_f32_e32 v114, v202, v114
	v_cvt_pk_bf16_f32 v120, v134, v179
	v_cvt_pk_bf16_f32 v121, v146, v177
	ds_read_b64_tr_b16 v[102:103], v193 offset:36864
	ds_read_b64_tr_b16 v[104:105], v193 offset:37376
	s_waitcnt lgkmcnt(4)
	v_mfma_f32_32x32x16_bf16 v[82:97], v[98:101], v[210:213], v[82:97]
	v_add_f32_e32 v110, v203, v114
	v_add_f32_e32 v110, v204, v110
	v_add_f32_e32 v110, v205, v110
	v_add_f32_e32 v110, v206, v110
	v_cvt_pk_bf16_f32 v114, v181, v202
	v_cvt_pk_bf16_f32 v115, v203, v204
	ds_read_b64_tr_b16 v[98:99], v193 offset:40960
	ds_read_b64_tr_b16 v[100:101], v193 offset:41472
	v_mfma_f32_32x32x16_bf16 v[66:81], v[130:133], v[210:213], v[66:81]
	v_add_f32_e32 v110, v207, v110
	v_add_f32_e32 v110, v208, v110
	v_cvt_pk_bf16_f32 v116, v205, v206
	v_cvt_pk_bf16_f32 v117, v207, v208
	s_waitcnt lgkmcnt(4)
	v_mfma_f32_32x32x16_bf16 v[2:17], v[126:129], v[106:109], v[2:17]
	v_add_f32_e32 v143, v143, v110
	ds_read_b64_tr_b16 v[110:111], v193 offset:45056
	ds_read_b64_tr_b16 v[112:113], v193 offset:45568
	s_nop 2
	v_max3_f32 v130, v82, v83, v66
	v_max3_f32 v131, v84, v85, v67
	v_max3_f32 v130, v130, v68, v69
	v_max3_f32 v106, v130, v86, v87
	v_max3_f32 v107, v131, v88, v89
	s_waitcnt lgkmcnt(4)
	v_mfma_f32_32x32x16_bf16 v[50:65], v[126:129], v[102:105], v[50:65]
	ds_read_b64_tr_b16 v[130:131], v193 offset:33792
	ds_read_b64_tr_b16 v[132:133], v193 offset:34304
	v_max3_f32 v106, v106, v70, v71
	v_max3_f32 v107, v107, v72, v73
	v_max3_f32 v106, v106, v90, v91
	v_max3_f32 v107, v107, v92, v93
	s_waitcnt lgkmcnt(4)
	v_mfma_f32_32x32x16_bf16 v[34:49], v[126:129], v[98:101], v[34:49]
	ds_read_b64_tr_b16 v[134:135], v193 offset:37888
	ds_read_b64_tr_b16 v[136:137], v193 offset:38400
	v_max3_f32 v102, v106, v74, v75
	v_max3_f32 v103, v107, v76, v77
	v_max3_f32 v102, v102, v94, v95
	v_max3_f32 v103, v103, v96, v97
	s_waitcnt lgkmcnt(4)
	v_mfma_f32_32x32x16_bf16 v[18:33], v[126:129], v[110:113], v[18:33]
	v_max3_f32 v98, v102, v78, v79
	v_max3_f32 v99, v103, v80, v81
	ds_read_b64_tr_b16 v[138:139], v193 offset:41984
	ds_read_b64_tr_b16 v[140:141], v193 offset:42496
	v_max_f32 v98, v98, v99
	s_nop 0
	v_mov_b32_e32 v99, v98
	s_nop 1
	v_permlane32_swap_b32_e32 v98, v99
	v_max_f32 v98, v98, v99
	s_nop 0
	v_cmp_lt_f32_e32 vcc, s49, v98
	s_cmp_lg_u64 vcc, 0
	s_cselect_b64 s[28:29], -1, 0
	s_cbranch_vccnz .LBB0_503

; __global__ void __launch_bounds__(NWAVES * 64, 2) mega_fwd(Args args) {
;     extern __shared__ __attribute__((aligned(16))) unsigned char lds[];
	.amdhsa_kernel _Z8mega_fwd4Args
		.amdhsa_group_segment_fixed_size 0
		.amdhsa_private_segment_fixed_size 0
		.amdhsa_kernarg_size 392
		.amdhsa_user_sgpr_count 2
		.amdhsa_user_sgpr_dispatch_ptr 0
		.amdhsa_user_sgpr_queue_ptr 0
		.amdhsa_user_sgpr_kernarg_segment_ptr 1
		.amdhsa_user_sgpr_dispatch_id 0
		.amdhsa_user_sgpr_kernarg_preload_length 0
		.amdhsa_user_sgpr_kernarg_preload_offset 0
		.amdhsa_user_sgpr_private_segment_size 0
		.amdhsa_uses_dynamic_stack 0
		.amdhsa_enable_private_segment 0
		.amdhsa_system_sgpr_workgroup_id_x 1
		.amdhsa_system_sgpr_workgroup_id_y 0
		.amdhsa_system_sgpr_workgroup_id_z 0
		.amdhsa_system_sgpr_workgroup_info 0
		.amdhsa_system_vgpr_workitem_id 0
		.amdhsa_next_free_vgpr 256
		.amdhsa_next_free_sgpr 98
		.amdhsa_accum_offset 256
		.amdhsa_reserve_vcc 1
		.amdhsa_float_round_mode_32 0
		.amdhsa_float_round_mode_16_64 0
		.amdhsa_float_denorm_mode_32 3
		.amdhsa_float_denorm_mode_16_64 3
		.amdhsa_dx10_clamp 1
		.amdhsa_ieee_mode 1
		.amdhsa_fp16_overflow 0
		.amdhsa_tg_split 0
		.amdhsa_exception_fp_ieee_invalid_op 0
		.amdhsa_exception_fp_denorm_src 0
		.amdhsa_exception_fp_ieee_div_zero 0
		.amdhsa_exception_fp_ieee_overflow 0
		.amdhsa_exception_fp_ieee_underflow 0
		.amdhsa_exception_fp_ieee_inexact 0
		.amdhsa_exception_int_div_zero 0
	.end_amdhsa_kernel

; __global__ void __launch_bounds__(NWAVES * 64, 2) mega_fwd(Args args) {
;     extern __shared__ __attribute__((aligned(16))) unsigned char lds[];
amdhsa.kernels:
  - .agpr_count:     0
    .args:
      - .offset:         0
        .size:           136
        .value_kind:     by_value
      - .offset:         136
        .size:           4
        .value_kind:     hidden_block_count_x
      - .offset:         140
        .size:           4
        .value_kind:     hidden_block_count_y
      - .offset:         144
        .size:           4
        .value_kind:     hidden_block_count_z
      - .offset:         148
        .size:           2
        .value_kind:     hidden_group_size_x
      - .offset:         150
        .size:           2
        .value_kind:     hidden_group_size_y
      - .offset:         152
        .size:           2
        .value_kind:     hidden_group_size_z
      - .offset:         154
        .size:           2
        .value_kind:     hidden_remainder_x
      - .offset:         156
        .size:           2
        .value_kind:     hidden_remainder_y
      - .offset:         158
        .size:           2
        .value_kind:     hidden_remainder_z
      - .offset:         176
        .size:           8
        .value_kind:     hidden_global_offset_x
      - .offset:         184
        .size:           8
        .value_kind:     hidden_global_offset_y
      - .offset:         192
        .size:           8
        .value_kind:     hidden_global_offset_z
      - .offset:         200
        .size:           2
        .value_kind:     hidden_grid_dims
      - .offset:         256
        .size:           4
        .value_kind:     hidden_dynamic_lds_size
    .group_segment_fixed_size: 0
    .kernarg_segment_align: 8
    .kernarg_segment_size: 392
    .language:       OpenCL C
    .language_version:
      - 2
      - 0
    .max_flat_workgroup_size: 512
    .name:           _Z8mega_fwd4Args
    .private_segment_fixed_size: 0
    .sgpr_count:     104
    .sgpr_spill_count: 24
    .symbol:         _Z8mega_fwd4Args.kd
    .uniform_work_group_size: 1
    .uses_dynamic_stack: false
    .vgpr_count:     256
    .vgpr_spill_count: 0
    .wavefront_size: 64
